# v45 plus: attention softmax subtracts via 16 packed v_pk_add_f32 (negated broadcast max) instead of 32 v_sub_f32, bit-identical
# baseline (speedup 1.0000x reference)
; #define MFMA(a, b, c) __builtin_amdgcn_mfma_f32_32x32x16_bf16((a), (b), (c), 0, 0, 0)
; DI void attn_item(const Params& p, int seq, int hd, int qblk, char* smem, int tid_) {
;     ...
;     float ps = 0.f;
; #pragma unroll
;     for (int kb2 = 0; kb2 < 2; kb2++)
; #pragma unroll
;       for (int i = 0; i < 16; i++) {
;         float pv = __builtin_amdgcn_exp2f(st[kb2][i] - m);
;         st[kb2][i] = pv;
;         ps += pv;
;       }
;     lsum += ps;
;     __builtin_amdgcn_sched_barrier(0);
; #pragma unroll
;     for (int g = 0; g < 16; g++) {
;       const int kb2 = g >> 3, c = (g >> 2) & 1;
;       unsigned pk[4];
; #pragma unroll
;       for (int j = 0; j < 4; j++) pk[j] = pack2(st[kb2][8 * c + 2 * j], st[kb2][8 * c + 2 * j + 1]);
;       u32x4 pu = {pk[0], pk[1], pk[2], pk[3]};
;       bf16x8 pf = __builtin_bit_cast(bf16x8, pu);
;       o[g & 3] = MFMA(vfr[g & 3], pf, o[g & 3]);
;       if (g + 4 < 16) vfr[g & 3] = VFRAG(g + 4);
;       __builtin_amdgcn_sched_barrier(0);
;     }
;     ...
;     if (kt + 1 < 32) {
;       u16* sKn = (u16*)(smem + ((kt + 1) & 1) * 45056);
;       u16* sVn = sKn + 64 * 200;
; #pragma unroll
;       for (int i = 0; i < 3; i++) *(u32x4*)(sKn + kl + 64 * i) = rk[i];
; #pragma unroll
;       for (int i = 0; i < 2; i++) *(u32x4*)(sVn + vl + 64 * i * 72) = rv[i];
;     }
;     __syncthreads();
;     if (kt + 2 < 32) {
; #pragma unroll
;       for (int i = 0; i < 3; i++) rk[i] = *(const u32x4*)(kg + (size_t)(kt + 2) * 64 * 768 + 64 * i);
; #pragma unroll
;       for (int i = 0; i < 2; i++) rv[i] = *(const u32x4*)(vg + (size_t)(64 * i) * 2048 + (kt + 2) * 64);
;     }
.LBB0_627:
	v_pk_add_f32 v[64:65], v[64:65], v[198:199] op_sel_hi:[1,0] neg_lo:[0,1] neg_hi:[0,1]
	v_pk_add_f32 v[66:67], v[66:67], v[198:199] op_sel_hi:[1,0] neg_lo:[0,1] neg_hi:[0,1]
	v_pk_add_f32 v[68:69], v[68:69], v[198:199] op_sel_hi:[1,0] neg_lo:[0,1] neg_hi:[0,1]
	v_pk_add_f32 v[70:71], v[70:71], v[198:199] op_sel_hi:[1,0] neg_lo:[0,1] neg_hi:[0,1]
	v_pk_add_f32 v[72:73], v[72:73], v[198:199] op_sel_hi:[1,0] neg_lo:[0,1] neg_hi:[0,1]
	v_pk_add_f32 v[74:75], v[74:75], v[198:199] op_sel_hi:[1,0] neg_lo:[0,1] neg_hi:[0,1]
	v_pk_add_f32 v[76:77], v[76:77], v[198:199] op_sel_hi:[1,0] neg_lo:[0,1] neg_hi:[0,1]
	v_pk_add_f32 v[78:79], v[78:79], v[198:199] op_sel_hi:[1,0] neg_lo:[0,1] neg_hi:[0,1]
	v_pk_add_f32 v[80:81], v[80:81], v[198:199] op_sel_hi:[1,0] neg_lo:[0,1] neg_hi:[0,1]
	v_pk_add_f32 v[82:83], v[82:83], v[198:199] op_sel_hi:[1,0] neg_lo:[0,1] neg_hi:[0,1]
	v_pk_add_f32 v[84:85], v[84:85], v[198:199] op_sel_hi:[1,0] neg_lo:[0,1] neg_hi:[0,1]
	v_pk_add_f32 v[86:87], v[86:87], v[198:199] op_sel_hi:[1,0] neg_lo:[0,1] neg_hi:[0,1]
	v_pk_add_f32 v[88:89], v[88:89], v[198:199] op_sel_hi:[1,0] neg_lo:[0,1] neg_hi:[0,1]
	v_pk_add_f32 v[90:91], v[90:91], v[198:199] op_sel_hi:[1,0] neg_lo:[0,1] neg_hi:[0,1]
	v_pk_add_f32 v[92:93], v[92:93], v[198:199] op_sel_hi:[1,0] neg_lo:[0,1] neg_hi:[0,1]
	v_pk_add_f32 v[94:95], v[94:95], v[198:199] op_sel_hi:[1,0] neg_lo:[0,1] neg_hi:[0,1]
	v_exp_f32_e32 v64, v64
	v_exp_f32_e32 v65, v65
	v_exp_f32_e32 v66, v66
	v_exp_f32_e32 v67, v67
	v_exp_f32_e32 v68, v68
	v_exp_f32_e32 v69, v69
	v_exp_f32_e32 v70, v70
	v_exp_f32_e32 v71, v71
	v_exp_f32_e32 v72, v72
	v_exp_f32_e32 v73, v73
	v_exp_f32_e32 v74, v74
	v_exp_f32_e32 v75, v75
	v_exp_f32_e32 v76, v76
	v_exp_f32_e32 v77, v77
	v_exp_f32_e32 v78, v78
	v_exp_f32_e32 v79, v79
	v_exp_f32_e32 v80, v80
	v_exp_f32_e32 v81, v81
	v_exp_f32_e32 v82, v82
	v_exp_f32_e32 v83, v83
	v_exp_f32_e32 v84, v84
	v_exp_f32_e32 v85, v85
	v_exp_f32_e32 v86, v86
	v_exp_f32_e32 v87, v87
	v_exp_f32_e32 v88, v88
	v_exp_f32_e32 v89, v89
	v_exp_f32_e32 v90, v90
	v_exp_f32_e32 v91, v91
	v_exp_f32_e32 v92, v92
	v_exp_f32_e32 v93, v93
	v_exp_f32_e32 v94, v94
	v_exp_f32_e32 v95, v95
	v_cvt_pk_bf16_f32 v200, v64, v65
	v_cvt_pk_bf16_f32 v201, v66, v67
	v_cvt_pk_bf16_f32 v202, v68, v69
	v_cvt_pk_bf16_f32 v203, v70, v71
	v_add3_u32 v199, s5, v195, v188
	s_waitcnt lgkmcnt(3)
	v_mfma_f32_32x32x16_bf16 v[48:63], v[176:179], v[200:203], v[48:63]
	v_add_f32_e32 v64, 0, v64
	v_add_f32_e32 v64, v65, v64
	ds_read_b128 v[176:179], v199 offset:25632
	s_waitcnt lgkmcnt(3)
	v_mfma_f32_32x32x16_bf16 v[32:47], v[172:175], v[200:203], v[32:47]
	v_add_f32_e32 v64, v66, v64
	v_add_f32_e32 v64, v67, v64
	ds_read_b128 v[172:175], v199 offset:30240
	s_waitcnt lgkmcnt(3)
	v_mfma_f32_32x32x16_bf16 v[16:31], v[168:171], v[200:203], v[16:31]
	v_add_f32_e32 v64, v68, v64
	v_add_f32_e32 v64, v69, v64
	ds_read_b128 v[168:171], v199 offset:34848
	s_waitcnt lgkmcnt(3)
	v_mfma_f32_32x32x16_bf16 v[0:15], v[164:167], v[200:203], v[0:15]
	v_add_f32_e32 v64, v70, v64
	v_add_f32_e32 v64, v71, v64
	ds_read_b128 v[164:167], v199 offset:39456
	v_cvt_pk_bf16_f32 v200, v72, v73
	v_cvt_pk_bf16_f32 v201, v74, v75
	v_cvt_pk_bf16_f32 v202, v76, v77
	v_cvt_pk_bf16_f32 v203, v78, v79
	s_waitcnt lgkmcnt(3)
	s_nop 0
	v_mfma_f32_32x32x16_bf16 v[48:63], v[176:179], v[200:203], v[48:63]
	v_add_f32_e32 v64, v72, v64
	v_add_f32_e32 v64, v73, v64
	ds_read_b128 v[176:179], v199 offset:25664
	s_waitcnt lgkmcnt(3)
	v_mfma_f32_32x32x16_bf16 v[32:47], v[172:175], v[200:203], v[32:47]
	v_add_f32_e32 v64, v74, v64
	v_add_f32_e32 v64, v75, v64
	ds_read_b128 v[172:175], v199 offset:30272
	s_waitcnt lgkmcnt(3)
	v_mfma_f32_32x32x16_bf16 v[16:31], v[168:171], v[200:203], v[16:31]
	v_add_f32_e32 v64, v76, v64
	v_add_f32_e32 v64, v77, v64
	ds_read_b128 v[168:171], v199 offset:34880
	s_waitcnt lgkmcnt(3)
	v_mfma_f32_32x32x16_bf16 v[0:15], v[164:167], v[200:203], v[0:15]
	v_add_f32_e32 v64, v78, v64
	v_add_f32_e32 v64, v79, v64
	ds_read_b128 v[164:167], v199 offset:39488
	v_cvt_pk_bf16_f32 v200, v80, v81
	v_cvt_pk_bf16_f32 v201, v82, v83
	v_cvt_pk_bf16_f32 v202, v84, v85
	v_cvt_pk_bf16_f32 v203, v86, v87
	s_waitcnt lgkmcnt(3)
	s_nop 0
	v_mfma_f32_32x32x16_bf16 v[48:63], v[176:179], v[200:203], v[48:63]
	v_add_f32_e32 v64, v80, v64
	v_add_f32_e32 v64, v81, v64
	ds_read_b128 v[176:179], v199 offset:25696
	s_waitcnt lgkmcnt(3)
	v_mfma_f32_32x32x16_bf16 v[32:47], v[172:175], v[200:203], v[32:47]
	v_add_f32_e32 v64, v82, v64
	v_add_f32_e32 v64, v83, v64
	ds_read_b128 v[172:175], v199 offset:30304
	s_waitcnt lgkmcnt(3)
	v_mfma_f32_32x32x16_bf16 v[16:31], v[168:171], v[200:203], v[16:31]
	v_add_f32_e32 v64, v84, v64
	v_add_f32_e32 v64, v85, v64
	ds_read_b128 v[168:171], v199 offset:34912
	s_waitcnt lgkmcnt(3)
	v_mfma_f32_32x32x16_bf16 v[0:15], v[164:167], v[200:203], v[0:15]
	v_add_f32_e32 v64, v86, v64
	v_add_f32_e32 v64, v87, v64
	ds_read_b128 v[164:167], v199 offset:39520
	v_cvt_pk_bf16_f32 v200, v88, v89
	v_cvt_pk_bf16_f32 v201, v90, v91
	v_cvt_pk_bf16_f32 v202, v92, v93
	v_cvt_pk_bf16_f32 v203, v94, v95
	s_waitcnt lgkmcnt(3)
	s_nop 0
	v_mfma_f32_32x32x16_bf16 v[48:63], v[176:179], v[200:203], v[48:63]
	v_add_f32_e32 v64, v88, v64
	v_add_f32_e32 v64, v89, v64
	s_waitcnt lgkmcnt(2)
	v_mfma_f32_32x32x16_bf16 v[32:47], v[172:175], v[200:203], v[32:47]
	v_add_f32_e32 v64, v90, v64
	v_add_f32_e32 v64, v91, v64
	s_waitcnt lgkmcnt(1)
	v_mfma_f32_32x32x16_bf16 v[16:31], v[168:171], v[200:203], v[16:31]
	v_add_f32_e32 v64, v92, v64
	v_add_f32_e32 v64, v93, v64
	s_waitcnt lgkmcnt(0)
	v_mfma_f32_32x32x16_bf16 v[0:15], v[164:167], v[200:203], v[0:15]
	v_add_f32_e32 v64, v94, v64
	v_add_f32_e32 v64, v95, v64
	s_add_i32 s5, s3, 1
	s_bitcmp1_b32 s5, 0
	s_cselect_b32 s1, 0xb000, 0
	s_add_i32 s1, s1, 0
	v_lshl_add_u32 v164, v182, 1, s1
	s_waitcnt vmcnt(4)
	ds_write_b128 v164, v[144:147]
	s_waitcnt vmcnt(3)
	ds_write_b128 v164, v[148:151] offset:128
	s_waitcnt vmcnt(2)
	ds_write_b128 v164, v[152:155] offset:256
	v_lshl_add_u32 v164, v196, 1, s1
	s_cmp_gt_u32 s3, 29
	s_waitcnt vmcnt(1)
	ds_write_b128 v164, v[156:159] offset:25600
	s_waitcnt vmcnt(0)
	ds_write_b128 v164, v[160:163] offset:34816
	s_waitcnt lgkmcnt(0)
	s_barrier
	s_cbranch_scc1 .LBB0_629
	global_load_dwordx4 v[144:147], v[186:187], off offset:-128
	global_load_dwordx4 v[148:151], v[186:187], off
	global_load_dwordx4 v[152:155], v[186:187], off offset:128
	global_load_dwordx4 v[156:159], v[184:185], off
	v_add_co_u32_e32 v160, vcc, 0x40000, v184
	s_nop 1
	v_addc_co_u32_e32 v161, vcc, 0, v185, vcc
	global_load_dwordx4 v[160:163], v[160:161], off
